# E sample-row tail: residual load issued before the split-K fragment loads
# speedup vs baseline: 1.0053x; 1.0005x over previous
; __device__ __forceinline__ u32x2 pack4(f32x4 v) { u32x2 r; r.x = cvt_pk(v[0], v[1]); r.y = cvt_pk(v[2], v[3]); return r; }
; __device__ __forceinline__ int lane_fresh() { int l; asm volatile("v_mbcnt_lo_u32_b32 %0, -1, 0\n\tv_mbcnt_hi_u32_b32 %0, -1, %0" : "=v"(l)); return l; }
; __device__ __forceinline__ float shfl_xor_f(float v, int mask) { const int l = lane_fresh(); return __int_as_float(__builtin_amdgcn_ds_bpermute((l ^ mask) << 2, __float_as_int(v))); }
; #define MFMA16(a, b, c) __builtin_amdgcn_mfma_f32_16x16x32_bf16((a), (b), (c), 0, 0, 0)
; template <int NT, class FA, class FB, class FL>
; __device__ __forceinline__ void skgemm(FA aptr, FB bptr, FL ldf, const int KS, const int wv) {
;     ...
;   for (int i = 0; i < NT; ++i) {
;     f32x4 acc = {0.f, 0.f, 0.f, 0.f};
;     const int ld = ldf(i);
;     const u16* ap = aptr(i) + (size_t)fr * ld + wv * KS + fq * 8;
;     const u16* bp = bptr(i) + (size_t)fr * ld + wv * KS + fq * 8;
; #pragma unroll 8
;     for (int k = 0; k < KS; k += 32) acc = MFMA16(*(const bf16x8*)(bp + k), *(const bf16x8*)(ap + k), acc);
;     *(f32x4*)(part + ((i * 8 + wv) * 64 + lane) * 4) = acc;
;   }
;   __syncthreads();
; __device__ __forceinline__ void phaseE(const Params& p, const int wv, const int rep) {
;     ...
;   for (int gb = blockIdx.x; gb < 256; gb += gridDim.x) {
;     const int task0 = gb * 2, mt = task0 >> 6, nt0 = task0 & 63;
;     const u16* Ab = MERGED + (size_t)(TP + mt * 16) * 1024;
;     skgemm<2>([&](int) { return Ab; }, [&](int i) { return WOUT + (size_t)((nt0 + i) * 16) * 1024; }, [&](int) { return 1024; }, 128, wv);
;     if (wv < 2) {
;       const int lane_e = lane_fresh(), fr = lane_e & 15, fq = lane_e >> 4;
;       const int ntl = nt0 + wv, row = TP + mt * 16 + fr, col = ntl * 16 + fq * 4;
;       f32x4 v = skreduce(wv) + *(const f32x4*)(p.in[1] + (size_t)(row - TP) * 1024 + col);
;       *(u32x2*)(H2B + (size_t)row * 1024 + col) = pack4(v);
;       float ss = v[0] * v[0] + v[1] * v[1] + v[2] * v[2] + v[3] * v[3];
;       ss += shfl_xor_f(ss, 16); ss += shfl_xor_f(ss, 32);
;       if (fq == 0) PSS[(size_t)(row - TP) * 64 + ntl] = ss;
.LBB0_1003:
	s_ashr_i32 s16, s23, 1
	s_and_b32 s16, s16, -16
	s_addk_i32 s16, 0x4000
	s_ashr_i32 s17, s16, 31
	s_and_b32 s0, s20, 62
	s_lshl_b64 s[24:25], s[16:17], 11
	v_mbcnt_lo_u32_b32 v44, -1, 0
	v_mbcnt_hi_u32_b32 v44, -1, v44
	s_add_u32 s24, s2, s24
	v_ashrrev_i32_e32 v0, 1, v44
	v_and_b32_e32 v2, -8, v0
	v_lshlrev_b32_e32 v0, 11, v44
	s_addc_u32 s25, s3, s25
	v_and_b32_e32 v0, 0x7800, v0
	s_lshl_b32 s17, s0, 15
	v_ashrrev_i32_e32 v3, 31, v2
	s_waitcnt lgkmcnt(0)
	v_lshl_add_u64 v[4:5], s[24:25], 0, v[0:1]
	s_add_u32 s24, s33, s17
	v_lshl_add_u64 v[4:5], v[4:5], 0, s[12:13]
	v_lshlrev_b64 v[2:3], 1, v[2:3]
	s_addc_u32 s25, s40, 0
	v_lshl_add_u64 v[38:39], v[4:5], 0, v[2:3]
	v_lshl_add_u64 v[4:5], s[24:25], 0, v[0:1]
	v_lshl_add_u64 v[4:5], v[4:5], 0, s[12:13]
	v_lshl_add_u64 v[40:41], v[4:5], 0, v[2:3]
	s_cmp_gt_u32 s90, 1
	s_cbranch_scc1 .Leh_skip
	s_or_b32 s100, s0, s90
	v_readlane_b32 s98, v251, 8
	v_readlane_b32 s99, v251, 9
	v_and_or_b32 v100, v44, 15, s16
	v_ashrrev_i32_e32 v102, 2, v44
	v_and_b32_e32 v102, -4, v102
	v_add_u32_e32 v100, 0xffffc000, v100
	v_ashrrev_i32_e32 v101, 31, v100
	v_lshl_add_u32 v102, s100, 4, v102
	v_ashrrev_i32_e32 v103, 31, v102
	v_lshlrev_b64 v[100:101], 12, v[100:101]
	v_lshl_add_u64 v[100:101], s[98:99], 0, v[100:101]
	v_lshl_add_u64 v[100:101], v[102:103], 2, v[100:101]
	global_load_dwordx4 v[104:107], v[100:101], off
.Leh_skip:
	s_barrier
	global_load_dwordx4 v[2:5], v[40:41], off
	global_load_dwordx4 v[6:9], v[38:39], off
	v_add_co_u32_e32 v22, vcc, s22, v40
	v_lshl_add_u64 v[42:43], v[40:41], 0, s[14:15]
	s_nop 0
	v_addc_co_u32_e32 v23, vcc, 0, v41, vcc
	global_load_dwordx4 v[10:13], v[22:23], off
	global_load_dwordx4 v[14:17], v[40:41], off offset:64
	global_load_dwordx4 v[18:21], v[38:39], off offset:64
	v_lshl_add_u32 v0, v44, 4, s18
	global_load_dwordx4 v[22:25], v[42:43], off offset:64
	global_load_dwordx4 v[26:29], v[40:41], off offset:128
	global_load_dwordx4 v[30:33], v[38:39], off offset:128
	global_load_dwordx4 v[34:37], v[42:43], off offset:192
	s_and_b64 vcc, exec, s[4:5]
	s_waitcnt vmcnt(7)
	v_mfma_f32_16x16x32_bf16 v[2:5], v[2:5], v[6:9], 0
	s_waitcnt vmcnt(6)
	v_mfma_f32_16x16x32_bf16 v[6:9], v[10:13], v[6:9], 0
	global_load_dwordx4 v[10:13], v[42:43], off offset:128
	s_waitcnt vmcnt(5)
	v_mfma_f32_16x16x32_bf16 v[2:5], v[14:17], v[18:21], v[2:5]
	global_load_dwordx4 v[14:17], v[40:41], off offset:192
	s_waitcnt vmcnt(5)
	v_mfma_f32_16x16x32_bf16 v[6:9], v[22:25], v[18:21], v[6:9]
	global_load_dwordx4 v[18:21], v[38:39], off offset:192
	s_waitcnt vmcnt(4)
	v_mfma_f32_16x16x32_bf16 v[2:5], v[26:29], v[30:33], v[2:5]
	s_waitcnt vmcnt(2)
	v_mfma_f32_16x16x32_bf16 v[6:9], v[10:13], v[30:33], v[6:9]
	s_waitcnt vmcnt(0)
	v_mfma_f32_16x16x32_bf16 v[2:5], v[14:17], v[18:21], v[2:5]
	v_mfma_f32_16x16x32_bf16 v[6:9], v[34:37], v[18:21], v[6:9]
	s_nop 6
	ds_write_b128 v0, v[2:5]
	ds_write_b128 v0, v[6:9] offset:8192
	s_waitcnt lgkmcnt(0)
	s_barrier
	s_cbranch_vccnz .LBB0_1002
	v_mbcnt_lo_u32_b32 v44, -1, 0
	v_mbcnt_hi_u32_b32 v44, -1, v44
	s_or_b32 s0, s0, s90
	v_and_or_b32 v40, v44, 15, s16
	v_ashrrev_i32_e32 v0, 2, v44
	v_add_u32_e32 v2, 0xffffc000, v40
	v_and_b32_e32 v0, -4, v0
	v_ashrrev_i32_e32 v3, 31, v2
	v_readlane_b32 s52, v251, 6
	v_lshl_add_u32 v42, s0, 4, v0
	v_lshlrev_b64 v[4:5], 12, v[2:3]
	v_readlane_b32 s54, v251, 8
	v_readlane_b32 s55, v251, 9
	v_ashrrev_i32_e32 v43, 31, v42
	v_mbcnt_lo_u32_b32 v0, -1, 0
	v_mbcnt_hi_u32_b32 v0, -1, v0
	v_ashrrev_i32_e32 v41, 31, v40
	v_lshl_add_u64 v[4:5], s[54:55], 0, v[4:5]
	v_lshl_add_u64 v[4:5], v[42:43], 2, v[4:5]
	v_mov_b32_e32 v4, v104
	v_mov_b32_e32 v5, v105
	v_mov_b32_e32 v6, v106
	v_mov_b32_e32 v7, v107
	v_lshl_add_u32 v0, v0, 4, s19
	ds_read_b128 v[8:11], v0
	ds_read_b128 v[12:15], v0 offset:1024
	ds_read_b128 v[16:19], v0 offset:2048
	ds_read_b128 v[20:23], v0 offset:3072
	ds_read_b128 v[24:27], v0 offset:4096
	ds_read_b128 v[28:31], v0 offset:5120
	ds_read_b128 v[32:35], v0 offset:6144
	ds_read_b128 v[36:39], v0 offset:7168
	s_waitcnt lgkmcnt(7)
	v_pk_add_f32 v[10:11], v[10:11], 0 op_sel_hi:[1,0]
	v_pk_add_f32 v[8:9], v[8:9], 0 op_sel_hi:[1,0]
	s_waitcnt lgkmcnt(6)
	v_pk_add_f32 v[10:11], v[10:11], v[14:15]
	v_pk_add_f32 v[8:9], v[8:9], v[12:13]
	s_waitcnt lgkmcnt(5)
	v_pk_add_f32 v[10:11], v[10:11], v[18:19]
	v_pk_add_f32 v[8:9], v[8:9], v[16:17]
	s_waitcnt lgkmcnt(4)
	v_pk_add_f32 v[10:11], v[10:11], v[22:23]
	v_pk_add_f32 v[8:9], v[8:9], v[20:21]
	s_waitcnt lgkmcnt(3)
	v_pk_add_f32 v[10:11], v[10:11], v[26:27]
	v_pk_add_f32 v[8:9], v[8:9], v[24:25]
	s_waitcnt lgkmcnt(2)
	v_pk_add_f32 v[10:11], v[10:11], v[30:31]
	v_pk_add_f32 v[8:9], v[8:9], v[28:29]
	s_waitcnt lgkmcnt(1)
	v_pk_add_f32 v[10:11], v[10:11], v[34:35]
	v_pk_add_f32 v[8:9], v[8:9], v[32:33]
	v_lshlrev_b64 v[40:41], 11, v[40:41]
	s_waitcnt lgkmcnt(0)
	v_pk_add_f32 v[10:11], v[10:11], v[38:39]
	v_pk_add_f32 v[8:9], v[8:9], v[36:37]
	v_lshl_add_u64 v[40:41], s[8:9], 0, v[40:41]
	v_lshl_add_u64 v[40:41], v[42:43], 1, v[40:41]
	v_cmp_gt_u32_e32 vcc, 16, v44
	v_readlane_b32 s53, v251, 7
	v_readlane_b32 s56, v251, 10
	v_readlane_b32 s57, v251, 11
	v_readlane_b32 s58, v251, 12
	v_readlane_b32 s59, v251, 13
	v_readlane_b32 s60, v251, 14
	v_readlane_b32 s61, v251, 15
	v_readlane_b32 s62, v251, 16
	v_readlane_b32 s63, v251, 17
	v_readlane_b32 s64, v251, 18
	v_readlane_b32 s65, v251, 19
	v_readlane_b32 s66, v251, 20
	v_readlane_b32 s67, v251, 21
	s_waitcnt vmcnt(0)
	v_pk_add_f32 v[6:7], v[10:11], v[6:7]
	v_pk_add_f32 v[4:5], v[8:9], v[4:5]
	v_cvt_pk_bf16_f32 v9, v6, v7
	v_cvt_pk_bf16_f32 v8, v4, v5
	v_mul_f32_e32 v0, v5, v5
	global_store_dwordx2 v[40:41], v[8:9], off
	v_fmac_f32_e32 v0, v4, v4
	v_mbcnt_lo_u32_b32 v4, -1, 0
	v_mbcnt_hi_u32_b32 v4, -1, v4
	v_fmac_f32_e32 v0, v6, v6
	v_lshlrev_b32_e32 v4, 2, v4
	v_fmac_f32_e32 v0, v7, v7
	v_xor_b32_e32 v4, 64, v4
	ds_bpermute_b32 v4, v4, v0
	v_mbcnt_lo_u32_b32 v5, -1, 0
	v_mbcnt_hi_u32_b32 v5, -1, v5
	s_waitcnt lgkmcnt(0)
	v_add_f32_e32 v0, v0, v4
	v_lshlrev_b32_e32 v5, 2, v5
	v_xor_b32_e32 v4, 0x80, v5
	ds_bpermute_b32 v4, v4, v0
	s_and_saveexec_b64 s[16:17], vcc
	s_cbranch_execz .LBB0_1001
	v_lshlrev_b64 v[2:3], 8, v[2:3]
	v_lshl_add_u64 v[2:3], s[10:11], 0, v[2:3]
	s_lshl_b32 s0, s0, 2
	s_waitcnt lgkmcnt(0)
	v_add_f32_e32 v0, v0, v4
	v_lshl_add_u64 v[2:3], v[2:3], 0, s[0:1]
	global_store_dword v[2:3], v0, off
	s_branch .LBB0_1001
